# final RMSNorm: loop-invariant gain loads hoisted out of the row loop, no vmcnt(0) between the four stores of a row
# speedup vs baseline: 1.0268x; 1.0008x over previous
.LBB0_500:
	s_and_b64 vcc, exec, s[26:27]
	s_cbranch_vccz .LBB0_504
	v_readlane_b32 s2, v255, 16
	s_ashr_i32 s2, s2, 6
	v_readlane_b32 s3, v252, 27
	s_add_i32 s38, s2, s3
	s_cmpk_gt_i32 s38, 0x7fff
	s_cbranch_scc1 .LBB0_504
	v_and_b32_e32 v0, 64, v222
	v_add_u32_e32 v0, 64, v0
	s_waitcnt lgkmcnt(0)
	v_xor_b32_e32 v2, 1, v222
	v_cmp_lt_i32_e32 vcc, v2, v0
	s_ashr_i32 s39, s38, 31
	s_lshl_b64 s[2:3], s[38:39], 11
	v_cndmask_b32_e32 v2, v222, v2, vcc
	v_lshlrev_b32_e32 v8, 2, v2
	v_xor_b32_e32 v2, 2, v222
	v_cmp_lt_i32_e32 vcc, v2, v0
	s_add_u32 s2, s14, s2
	v_lshlrev_b32_e32 v4, 3, v229
	v_cndmask_b32_e32 v2, v222, v2, vcc
	v_lshlrev_b32_e32 v9, 2, v2
	v_xor_b32_e32 v2, 4, v222
	v_cmp_lt_i32_e32 vcc, v2, v0
	v_mov_b32_e32 v5, v1
	s_addc_u32 s3, s15, s3
	v_cndmask_b32_e32 v2, v222, v2, vcc
	v_lshlrev_b32_e32 v10, 2, v2
	v_xor_b32_e32 v2, 8, v222
	v_cmp_lt_i32_e32 vcc, v2, v0
	v_lshl_add_u64 v[4:5], s[2:3], 0, v[4:5]
	s_lshl_b64 s[2:3], s[38:39], 12
	v_cndmask_b32_e32 v2, v222, v2, vcc
	v_lshlrev_b32_e32 v11, 2, v2
	v_xor_b32_e32 v2, 16, v222
	v_cmp_lt_i32_e32 vcc, v2, v0
	v_readlane_b32 s6, v254, 34
	v_readlane_b32 s16, v252, 0
	v_cndmask_b32_e32 v2, v222, v2, vcc
	v_lshlrev_b32_e32 v12, 2, v2
	v_xor_b32_e32 v2, 32, v222
	v_cmp_lt_i32_e32 vcc, v2, v0
	s_add_u32 s2, s6, s2
	v_readlane_b32 s6, v254, 35
	v_cndmask_b32_e32 v0, v222, v2, vcc
	v_lshlrev_b32_e32 v13, 2, v0
	v_lshlrev_b32_e32 v0, 4, v229
	v_readlane_b32 s17, v252, 1
	s_addc_u32 s3, s6, s3
	v_lshl_add_u64 v[6:7], s[2:3], 0, v[0:1]
	v_lshl_add_u64 v[2:3], s[16:17], 0, v[0:1]
	v_readlane_b32 s2, v255, 4
	v_readlane_b32 s10, v254, 32
	v_readlane_b32 s16, v254, 36
	s_mov_b32 s6, s2
	v_readlane_b32 s11, v254, 33
	v_readlane_b32 s17, v254, 37
	v_readlane_b32 s18, v252, 2
	v_readlane_b32 s19, v252, 3
	v_readlane_b32 s3, v255, 5
	global_load_dwordx4 v[100:103], v[2:3], off
	global_load_dwordx4 v[104:107], v[2:3], off offset:1024
	global_load_dwordx4 v[108:111], v[2:3], off offset:2048
	global_load_dwordx4 v[112:115], v[2:3], off offset:3072
.LBB0_503:
	global_load_dwordx2 v[18:19], v[4:5], off
	global_load_dwordx2 v[20:21], v[4:5], off offset:512
	global_load_dwordx2 v[22:23], v[4:5], off offset:1024
	global_load_dwordx2 v[24:25], v[4:5], off offset:1536
	s_add_i32 s38, s38, s6
	v_lshl_add_u64 v[4:5], v[4:5], 0, s[10:11]
	s_cmpk_gt_i32 s38, 0x7fff
	s_waitcnt vmcnt(3)
	v_lshlrev_b32_e32 v26, 16, v18
	v_and_b32_e32 v27, 0xffff0000, v18
	v_lshlrev_b32_e32 v18, 16, v19
	v_and_b32_e32 v19, 0xffff0000, v19
	s_waitcnt vmcnt(2)
	v_lshlrev_b32_e32 v29, 16, v21
	v_lshlrev_b32_e32 v28, 16, v20
	v_and_b32_e32 v21, 0xffff0000, v21
	v_and_b32_e32 v20, 0xffff0000, v20
	s_waitcnt vmcnt(1)
	v_lshlrev_b32_e32 v30, 16, v22
	v_and_b32_e32 v31, 0xffff0000, v22
	v_lshlrev_b32_e32 v22, 16, v23
	v_and_b32_e32 v23, 0xffff0000, v23
	s_waitcnt vmcnt(0)
	v_lshlrev_b32_e32 v33, 16, v24
	v_mul_f32_e32 v0, v19, v19
	v_mul_f32_e32 v32, v27, v27
	v_pk_mul_f32 v[36:37], v[20:21], v[20:21]
	v_mov_b32_e32 v39, v33
	v_mul_f32_e32 v38, v23, v23
	v_pk_fma_f32 v[40:41], v[18:19], v[18:19], v[0:1] op_sel_hi:[1,1,0]
	v_pk_fma_f32 v[42:43], v[26:27], v[26:27], v[32:33] op_sel_hi:[1,1,0]
	v_and_b32_e32 v35, 0xffff0000, v24
	v_lshlrev_b32_e32 v24, 16, v25
	v_and_b32_e32 v25, 0xffff0000, v25
	v_mul_f32_e32 v34, v31, v31
	v_pk_fma_f32 v[36:37], v[28:29], v[28:29], v[36:37]
	v_pk_fma_f32 v[46:47], v[22:23], v[22:23], v[38:39] op_sel_hi:[1,1,0]
	v_mov_b32_e32 v32, v42
	v_mov_b32_e32 v38, v40
	v_mul_f32_e32 v48, v35, v35
	v_mul_f32_e32 v49, v24, v24
	v_mul_f32_e32 v50, v25, v25
	v_pk_fma_f32 v[44:45], v[30:31], v[30:31], v[34:35] op_sel_hi:[1,1,0]
	v_pk_add_f32 v[40:41], v[42:43], v[40:41]
	v_pk_add_f32 v[36:37], v[36:37], v[36:37] op_sel:[0,1] op_sel_hi:[1,0]
	v_pk_mul_f32 v[38:39], v[32:33], v[38:39]
	v_mov_b32_e32 v45, v49
	v_mov_b32_e32 v47, v50
	v_mov_b32_e32 v37, v48
	v_mov_b32_e32 v41, v39
	v_pk_add_f32 v[42:43], v[44:45], v[46:47]
	v_pk_add_f32 v[36:37], v[40:41], v[36:37]
	s_nop 0
	v_pk_add_f32 v[36:37], v[36:37], v[42:43]
	s_nop 0
	v_add_f32_e32 v0, v36, v37
	ds_bpermute_b32 v32, v8, v0
	s_waitcnt lgkmcnt(0)
	v_add_f32_e32 v0, v0, v32
	ds_bpermute_b32 v32, v9, v0
	s_waitcnt lgkmcnt(0)
	v_add_f32_e32 v0, v0, v32
	ds_bpermute_b32 v32, v10, v0
	s_waitcnt lgkmcnt(0)
	v_add_f32_e32 v0, v0, v32
	ds_bpermute_b32 v32, v11, v0
	s_waitcnt lgkmcnt(0)
	v_add_f32_e32 v0, v0, v32
	ds_bpermute_b32 v32, v12, v0
	s_waitcnt lgkmcnt(0)
	v_add_f32_e32 v0, v0, v32
	ds_bpermute_b32 v32, v13, v0
	s_waitcnt lgkmcnt(0)
	v_add_f32_e32 v0, v0, v32
	v_fmamk_f32 v0, v0, 0x3a800000, v218
	v_mul_f32_e32 v32, 0x4f800000, v0
	v_cmp_gt_f32_e32 vcc, s55, v0
	s_nop 1
	v_cndmask_b32_e32 v0, v0, v32, vcc
	v_sqrt_f32_e32 v32, v0
	s_nop 0
	v_add_u32_e32 v34, -1, v32
	v_add_u32_e32 v36, 1, v32
	v_fma_f32 v37, -v34, v32, v0
	v_fma_f32 v38, -v36, v32, v0
	v_cmp_ge_f32_e64 s[36:37], 0, v37
	s_nop 1
	v_cndmask_b32_e64 v32, v32, v34, s[36:37]
	v_cmp_lt_f32_e64 s[36:37], 0, v38
	s_nop 1
	v_cndmask_b32_e64 v32, v32, v36, s[36:37]
	v_mul_f32_e32 v34, 0x37800000, v32
	v_cndmask_b32_e32 v32, v32, v34, vcc
	v_cmp_class_f32_e32 vcc, v0, v219
	s_nop 1
	v_cndmask_b32_e32 v0, v32, v0, vcc
	v_div_scale_f32 v32, s[2:3], v0, v0, 1.0
	v_rcp_f32_e32 v36, v32
	v_div_scale_f32 v34, vcc, 1.0, v0, 1.0
	v_fma_f32 v37, -v32, v36, 1.0
	v_fmac_f32_e32 v36, v37, v36
	v_mul_f32_e32 v37, v34, v36
	v_fma_f32 v38, -v32, v37, v34
	v_fmac_f32_e32 v37, v38, v36
	v_fma_f32 v32, -v32, v37, v34
	v_div_fmas_f32 v32, v32, v36, v37
	v_div_fixup_f32 v0, v32, v0, 1.0
	v_pk_mul_f32 v[26:27], v[0:1], v[26:27] op_sel_hi:[0,1]
	v_pk_mul_f32 v[18:19], v[0:1], v[18:19] op_sel_hi:[0,1]
	v_pk_mul_f32 v[16:17], v[18:19], v[102:103]
	v_pk_mul_f32 v[14:15], v[26:27], v[100:101]
	global_store_dwordx4 v[6:7], v[14:17], off offset:-3072
	s_nop 1
	v_mov_b32_e32 v18, v29
	v_mov_b32_e32 v19, v21
	v_mov_b32_e32 v29, v20
	v_pk_mul_f32 v[18:19], v[0:1], v[18:19] op_sel_hi:[0,1]
	v_pk_mul_f32 v[20:21], v[0:1], v[28:29] op_sel_hi:[0,1]
	v_mov_b32_e32 v34, v33
	v_pk_mul_f32 v[14:15], v[20:21], v[104:105]
	v_pk_mul_f32 v[16:17], v[18:19], v[106:107]
	global_store_dwordx4 v[6:7], v[14:17], off offset:-2048
	s_nop 1
	v_pk_mul_f32 v[18:19], v[0:1], v[22:23] op_sel_hi:[0,1]
	v_pk_mul_f32 v[20:21], v[0:1], v[30:31] op_sel_hi:[0,1]
	v_pk_mul_f32 v[14:15], v[20:21], v[108:109]
	v_pk_mul_f32 v[16:17], v[18:19], v[110:111]
	global_store_dwordx4 v[6:7], v[14:17], off offset:-1024
	s_nop 1
	v_pk_mul_f32 v[18:19], v[0:1], v[24:25] op_sel_hi:[0,1]
	v_pk_mul_f32 v[20:21], v[0:1], v[34:35] op_sel_hi:[0,1]
	v_pk_mul_f32 v[14:15], v[20:21], v[112:113]
	v_pk_mul_f32 v[16:17], v[18:19], v[114:115]
	global_store_dwordx4 v[6:7], v[14:17], off
	s_nop 1
	v_lshl_add_u64 v[6:7], v[6:7], 0, s[16:17]
	s_cbranch_scc0 .LBB0_503
